# stale vmcnt waits removed from the E4 MLA QK cluster (Q-fragment guards) and the O3 mid-stage mask test (on v5)
# baseline (speedup 1.0000x reference)
; #define LAS __attribute__((address_space(3)))
; __device__ __forceinline__ int crow(int r, int hi) { return (r & 3) + 8 * (r >> 2) + 4 * hi; }
; template <int DQK, int DV, int MODE, bool QNORM, int SK, int NQ> ...
;     ...
;             __builtin_amdgcn_s_setprio(1);
; #pragma unroll
;             for (int d0 = 0; d0 < DQK / 16; ++d0)
; #pragma unroll
;                 for (int sub = 0; sub < NSUB; ++sub) {
;                     const bf16x8 kf = *(const LAS bf16x8*)(sb + (sub * 32 + r32) * KP + hi * 16 + d0 * 32);
; #pragma unroll
;                     for (int qh = 0; qh < NQ; ++qh) sc[qh][sub] = __builtin_amdgcn_mfma_f32_32x32x16_bf16(kf, qf[qh][d0], sc[qh][sub], 0, 0, 0);
;                 }
;             }
;     ...
;                 } else if (MODE == 1) {
;                     const unsigned w = sub ? wcur1 : wcur0;
; #pragma unroll
;                     for (int r = 0; r < 16; ++r) { if (((w >> crow(r, hi)) & 1u) == 0u) {
; #pragma unroll
;                         for (int qh = 0; qh < NQ; ++qh) sc[qh][sub][r] = -INFINITY; } }
;                 } else if (st >= nst_w) {
; #pragma unroll
;                     for (int qh = 0; qh < NQ; ++qh)
; #pragma unroll
;                         for (int r = 0; r < 16; ++r) sc[qh][sub][r] = -INFINITY;
;                 }
;             }
;             bf16x8 pf[NQ][NSUB][2];
; #pragma unroll
;             for (int qh = 0; qh < NQ; ++qh) {
;                 float tm = sc[qh][0][0];
; #pragma unroll
;                 for (int sub = 0; sub < NSUB; ++sub)
; #pragma unroll
;                     for (int r = 0; r < 16; ++r) tm = fmaxf(tm, sc[qh][sub][r]);
;                 tm = fmaxf(tm, __shfl_xor(tm, 32));
;                 if (__ballot(tm > 0.f) != 0ull) {
.LBB0_3901:
	s_bitcmp1_b32 s8, 0
	s_cselect_b32 s0, 0x4800, 0
	v_xor_b32_e32 v66, 0x80000000, v248
	s_add_i32 s85, s0, 0
	v_xor_b32_e32 v98, 0x80000000, v247
	v_mov_b32_e32 v67, v66
	v_mov_b32_e32 v68, v66
	v_mov_b32_e32 v69, v66
	v_mov_b32_e32 v70, v66
	v_mov_b32_e32 v71, v66
	v_mov_b32_e32 v72, v66
	v_mov_b32_e32 v73, v66
	v_mov_b32_e32 v74, v66
	v_mov_b32_e32 v75, v66
	v_mov_b32_e32 v76, v66
	v_mov_b32_e32 v77, v66
	v_mov_b32_e32 v78, v66
	v_mov_b32_e32 v79, v66
	v_mov_b32_e32 v80, v66
	v_mov_b32_e32 v81, v66
	v_mov_b32_e32 v99, v98
	v_mov_b32_e32 v100, v98
	v_mov_b32_e32 v101, v98
	v_mov_b32_e32 v102, v98
	v_mov_b32_e32 v103, v98
	v_mov_b32_e32 v104, v98
	v_mov_b32_e32 v105, v98
	v_mov_b32_e32 v106, v98
	v_mov_b32_e32 v107, v98
	v_mov_b32_e32 v108, v98
	v_mov_b32_e32 v109, v98
	v_mov_b32_e32 v110, v98
	v_mov_b32_e32 v111, v98
	v_mov_b32_e32 v112, v98
	v_mov_b32_e32 v113, v98
	s_setprio 1
	v_add3_u32 v190, s85, v170, v171
	ds_read_b128 v[186:189], v190
	s_waitcnt lgkmcnt(0)
	v_mfma_f32_32x32x16_bf16 v[114:129], v[186:189], v[130:133], v[98:113]
	v_mfma_f32_32x32x16_bf16 v[82:97], v[186:189], v[146:149], v[66:81]
	ds_read_b128 v[186:189], v190 offset:4608
	s_waitcnt lgkmcnt(0)
	v_mfma_f32_32x32x16_bf16 v[98:113], v[186:189], v[130:133], v[98:113]
	v_mfma_f32_32x32x16_bf16 v[66:81], v[186:189], v[146:149], v[66:81]
	ds_read_b128 v[186:189], v190 offset:32
	s_waitcnt lgkmcnt(0)
	v_mfma_f32_32x32x16_bf16 v[114:129], v[186:189], v[134:137], v[114:129]
	v_mfma_f32_32x32x16_bf16 v[82:97], v[186:189], v[150:153], v[82:97]
	ds_read_b128 v[186:189], v190 offset:4640
	s_waitcnt lgkmcnt(0)
	v_mfma_f32_32x32x16_bf16 v[98:113], v[186:189], v[134:137], v[98:113]
	v_mfma_f32_32x32x16_bf16 v[66:81], v[186:189], v[150:153], v[66:81]
	ds_read_b128 v[186:189], v190 offset:64
	s_waitcnt lgkmcnt(0)
	v_mfma_f32_32x32x16_bf16 v[114:129], v[186:189], v[138:141], v[114:129]
	v_mfma_f32_32x32x16_bf16 v[82:97], v[186:189], v[154:157], v[82:97]
	ds_read_b128 v[186:189], v190 offset:4672
	s_waitcnt lgkmcnt(0)
	v_mfma_f32_32x32x16_bf16 v[98:113], v[186:189], v[138:141], v[98:113]
	v_mfma_f32_32x32x16_bf16 v[66:81], v[186:189], v[154:157], v[66:81]
	ds_read_b128 v[186:189], v190 offset:96
	s_waitcnt lgkmcnt(0)
	v_mfma_f32_32x32x16_bf16 v[114:129], v[186:189], v[142:145], v[114:129]
	v_mfma_f32_32x32x16_bf16 v[82:97], v[186:189], v[158:161], v[82:97]
	ds_read_b128 v[186:189], v190 offset:4704
	s_waitcnt lgkmcnt(0)
	v_mfma_f32_32x32x16_bf16 v[98:113], v[186:189], v[142:145], v[98:113]
	v_mfma_f32_32x32x16_bf16 v[66:81], v[186:189], v[158:161], v[66:81]
	s_setprio 0
	s_nop 0
	v_and_b32_e32 v186, v245, v203
	v_cmp_eq_u32_e64 s[0:1], 0, v186
	v_and_b32_e32 v186, v245, v204
	v_cmp_eq_u32_e64 s[70:71], 0, v186
	v_and_b32_e32 v186, v245, v205
	v_cmp_eq_u32_e64 s[8:9], 0, v186
	v_and_b32_e32 v186, v245, v206
	v_cmp_eq_u32_e64 s[10:11], 0, v186
	v_and_b32_e32 v186, v245, v207
	v_cmp_eq_u32_e64 s[12:13], 0, v186
	v_and_b32_e32 v186, v245, v208
	v_cmp_eq_u32_e64 s[14:15], 0, v186
	v_and_b32_e32 v186, v245, v209
	v_cmp_eq_u32_e64 s[16:17], 0, v186
	v_and_b32_e32 v186, v245, v210
	v_cmp_eq_u32_e64 s[18:19], 0, v186
	v_and_b32_e32 v186, v245, v211
	v_cmp_eq_u32_e64 s[20:21], 0, v186
	v_and_b32_e32 v186, v245, v212
	v_cmp_eq_u32_e64 s[22:23], 0, v186
	v_and_b32_e32 v186, v245, v213
	v_cmp_eq_u32_e64 s[24:25], 0, v186
	v_and_b32_e32 v186, v245, v214
	v_cmp_eq_u32_e64 s[26:27], 0, v186
	v_and_b32_e32 v186, v245, v215
	v_cmp_eq_u32_e64 s[28:29], 0, v186
	v_and_b32_e32 v186, v245, v216
	v_cmp_eq_u32_e64 s[30:31], 0, v186
	v_and_b32_e32 v186, v245, v217
	v_cmp_eq_u32_e64 s[34:35], 0, v186
	v_and_b32_e32 v186, v245, v218
	v_cmp_eq_u32_e64 s[36:37], 0, v186
	v_and_b32_e32 v186, v246, v203
	v_cmp_eq_u32_e64 s[38:39], 0, v186
	v_cndmask_b32_e64 v114, v114, v238, s[0:1]
	v_cndmask_b32_e64 v115, v115, v238, s[70:71]
	v_cndmask_b32_e64 v186, v98, v238, s[38:39]
	v_and_b32_e32 v98, v246, v204
	v_cmp_eq_u32_e64 s[40:41], 0, v98
	v_and_b32_e32 v98, v246, v205
	v_cmp_eq_u32_e64 s[42:43], 0, v98
	v_and_b32_e32 v98, v246, v206
	v_cmp_eq_u32_e64 s[44:45], 0, v98
	v_and_b32_e32 v98, v246, v207
	v_cmp_eq_u32_e64 s[46:47], 0, v98
	v_and_b32_e32 v98, v246, v208
	v_cmp_eq_u32_e64 s[48:49], 0, v98
	v_and_b32_e32 v98, v246, v209
	v_cmp_eq_u32_e64 s[50:51], 0, v98
	v_and_b32_e32 v98, v246, v210
	v_cmp_eq_u32_e64 s[52:53], 0, v98
	v_and_b32_e32 v98, v246, v211
	v_cmp_eq_u32_e64 s[54:55], 0, v98
	v_and_b32_e32 v98, v246, v212
	v_cmp_eq_u32_e64 s[56:57], 0, v98
	v_and_b32_e32 v98, v246, v213
	v_cmp_eq_u32_e64 s[58:59], 0, v98
	v_and_b32_e32 v98, v246, v214
	v_cmp_eq_u32_e64 s[60:61], 0, v98
	v_and_b32_e32 v98, v246, v215
	v_cmp_eq_u32_e64 s[62:63], 0, v98
	v_and_b32_e32 v98, v246, v216
	v_cmp_eq_u32_e64 s[64:65], 0, v98
	v_and_b32_e32 v98, v246, v217
	v_cmp_eq_u32_e64 s[66:67], 0, v98
	v_and_b32_e32 v98, v246, v218
	v_cndmask_b32_e64 v187, v99, v238, s[40:41]
	v_cmp_eq_u32_e64 s[68:69], 0, v98
	v_max_f32_e32 v98, v115, v115
	v_max_f32_e32 v99, v114, v114
	v_cndmask_b32_e64 v116, v116, v238, s[8:9]
	v_cndmask_b32_e64 v117, v117, v238, s[10:11]
	v_max_f32_e32 v98, v99, v98
	v_cndmask_b32_e64 v118, v118, v238, s[12:13]
	v_cndmask_b32_e64 v119, v119, v238, s[14:15]
	v_max3_f32 v98, v98, v116, v117
	v_cndmask_b32_e64 v120, v120, v238, s[16:17]
	v_cndmask_b32_e64 v121, v121, v238, s[18:19]
	v_max3_f32 v98, v98, v118, v119
	v_cndmask_b32_e64 v122, v122, v238, s[20:21]
	v_cndmask_b32_e64 v123, v123, v238, s[22:23]
	v_max3_f32 v98, v98, v120, v121
	v_cndmask_b32_e64 v124, v124, v238, s[24:25]
	v_cndmask_b32_e64 v125, v125, v238, s[26:27]
	v_max3_f32 v98, v98, v122, v123
	v_cndmask_b32_e64 v126, v126, v238, s[28:29]
	v_cndmask_b32_e64 v127, v127, v238, s[30:31]
	v_max3_f32 v98, v98, v124, v125
	v_cndmask_b32_e64 v128, v128, v238, s[34:35]
	v_cndmask_b32_e64 v129, v129, v238, s[36:37]
	v_max3_f32 v98, v98, v126, v127
	v_max3_f32 v98, v98, v128, v129
	v_cndmask_b32_e64 v188, v100, v238, s[42:43]
	v_cndmask_b32_e64 v189, v101, v238, s[44:45]
	v_max3_f32 v98, v98, v186, v187
	v_cndmask_b32_e64 v190, v102, v238, s[46:47]
	v_cndmask_b32_e64 v191, v103, v238, s[48:49]
	v_max3_f32 v98, v98, v188, v189
	v_cndmask_b32_e64 v192, v104, v238, s[50:51]
	v_cndmask_b32_e64 v193, v105, v238, s[52:53]
	v_max3_f32 v98, v98, v190, v191
	v_cndmask_b32_e64 v194, v106, v238, s[54:55]
	v_cndmask_b32_e64 v195, v107, v238, s[56:57]
	v_max3_f32 v98, v98, v192, v193
	v_cndmask_b32_e64 v196, v108, v238, s[58:59]
	v_cndmask_b32_e64 v197, v109, v238, s[60:61]
	v_max3_f32 v98, v98, v194, v195
	v_cndmask_b32_e64 v198, v110, v238, s[62:63]
	v_cndmask_b32_e64 v199, v111, v238, s[64:65]
	v_max3_f32 v98, v98, v196, v197
	v_cndmask_b32_e64 v200, v112, v238, s[66:67]
	v_cndmask_b32_e64 v201, v113, v238, s[68:69]
	v_max3_f32 v98, v98, v198, v199
	v_max3_f32 v98, v98, v200, v201
	ds_bpermute_b32 v99, v222, v98
	s_waitcnt lgkmcnt(0)
	v_max_f32_e32 v99, v99, v99
	v_max_f32_e32 v98, v98, v99
	v_cmp_lt_f32_e32 vcc, 0, v98
	s_cbranch_vccz .LBB0_3903
; template <int DQK, int DV, int MODE, bool QNORM, int SK, int NQ> ...
;     ...
;                 if (__ballot(tm > 0.f) != 0ull) {
;                     const float dl = fmaxf(tm, 0.f); m_run[qh] += dl;
;                     const float alpha = __builtin_amdgcn_exp2f(-dl);
;                     l_run[qh] *= alpha;
; #pragma unroll
;                     for (int sub = 0; sub < NSUB; ++sub)
; #pragma unroll
;                         for (int r = 0; r < 16; ++r) sc[qh][sub][r] -= dl;
; #pragma unroll
;                     for (int dt = 0; dt < DV / 32; ++dt)
; #pragma unroll
;                         for (int r = 0; r < 16; ++r) o[qh][dt][r] *= alpha;
;                 }
	v_max_f32_e32 v98, v98, v98
	v_max_f32_e32 v98, 0, v98
	v_exp_f32_e64 v100, -v98
	v_add_f32_e32 v247, v247, v98
	v_pk_add_f32 v[114:115], v[114:115], v[98:99] op_sel_hi:[1,0] neg_lo:[0,1] neg_hi:[0,1]
	v_pk_add_f32 v[116:117], v[116:117], v[98:99] op_sel_hi:[1,0] neg_lo:[0,1] neg_hi:[0,1]
	v_mul_f32_e32 v183, v183, v100
	v_pk_add_f32 v[118:119], v[118:119], v[98:99] op_sel_hi:[1,0] neg_lo:[0,1] neg_hi:[0,1]
	v_pk_add_f32 v[120:121], v[120:121], v[98:99] op_sel_hi:[1,0] neg_lo:[0,1] neg_hi:[0,1]
	v_pk_add_f32 v[122:123], v[122:123], v[98:99] op_sel_hi:[1,0] neg_lo:[0,1] neg_hi:[0,1]
	v_pk_add_f32 v[124:125], v[124:125], v[98:99] op_sel_hi:[1,0] neg_lo:[0,1] neg_hi:[0,1]
	v_pk_add_f32 v[126:127], v[126:127], v[98:99] op_sel_hi:[1,0] neg_lo:[0,1] neg_hi:[0,1]
	v_pk_add_f32 v[128:129], v[128:129], v[98:99] op_sel_hi:[1,0] neg_lo:[0,1] neg_hi:[0,1]
	v_pk_add_f32 v[186:187], v[186:187], v[98:99] op_sel_hi:[1,0] neg_lo:[0,1] neg_hi:[0,1]
	v_pk_add_f32 v[188:189], v[188:189], v[98:99] op_sel_hi:[1,0] neg_lo:[0,1] neg_hi:[0,1]
	v_pk_add_f32 v[190:191], v[190:191], v[98:99] op_sel_hi:[1,0] neg_lo:[0,1] neg_hi:[0,1]
	v_pk_add_f32 v[192:193], v[192:193], v[98:99] op_sel_hi:[1,0] neg_lo:[0,1] neg_hi:[0,1]
	v_pk_add_f32 v[194:195], v[194:195], v[98:99] op_sel_hi:[1,0] neg_lo:[0,1] neg_hi:[0,1]
	v_pk_add_f32 v[196:197], v[196:197], v[98:99] op_sel_hi:[1,0] neg_lo:[0,1] neg_hi:[0,1]
	v_pk_add_f32 v[198:199], v[198:199], v[98:99] op_sel_hi:[1,0] neg_lo:[0,1] neg_hi:[0,1]
	v_pk_add_f32 v[200:201], v[200:201], v[98:99] op_sel_hi:[1,0] neg_lo:[0,1] neg_hi:[0,1]
	v_pk_mul_f32 v[64:65], v[64:65], v[100:101] op_sel_hi:[1,0]
	v_pk_mul_f32 v[62:63], v[62:63], v[100:101] op_sel_hi:[1,0]
	v_pk_mul_f32 v[60:61], v[60:61], v[100:101] op_sel_hi:[1,0]
	v_pk_mul_f32 v[58:59], v[58:59], v[100:101] op_sel_hi:[1,0]
	v_pk_mul_f32 v[56:57], v[56:57], v[100:101] op_sel_hi:[1,0]
	v_pk_mul_f32 v[54:55], v[54:55], v[100:101] op_sel_hi:[1,0]
	v_pk_mul_f32 v[52:53], v[52:53], v[100:101] op_sel_hi:[1,0]
	v_pk_mul_f32 v[50:51], v[50:51], v[100:101] op_sel_hi:[1,0]
	v_pk_mul_f32 v[48:49], v[48:49], v[100:101] op_sel_hi:[1,0]
	v_pk_mul_f32 v[46:47], v[46:47], v[100:101] op_sel_hi:[1,0]
	v_pk_mul_f32 v[44:45], v[44:45], v[100:101] op_sel_hi:[1,0]
	v_pk_mul_f32 v[42:43], v[42:43], v[100:101] op_sel_hi:[1,0]
	v_pk_mul_f32 v[40:41], v[40:41], v[100:101] op_sel_hi:[1,0]
	v_pk_mul_f32 v[38:39], v[38:39], v[100:101] op_sel_hi:[1,0]
	v_pk_mul_f32 v[36:37], v[36:37], v[100:101] op_sel_hi:[1,0]
	v_pk_mul_f32 v[34:35], v[34:35], v[100:101] op_sel_hi:[1,0]

; #define LAS __attribute__((address_space(3)))
; __device__ __forceinline__ int crow(int r, int hi) { return (r & 3) + 8 * (r >> 2) + 4 * hi; }
; template <int DQK, int DV, int MODE, bool QNORM, int SK, int NQ> ...
;     ...
;             if (NQ == 1 && DQK <= 96) {
;                 bf16x8 kfa[NSUB][DQK / 16];
; #pragma unroll
;                 for (int d0 = 0; d0 < DQK / 16; ++d0)
; #pragma unroll
;                     for (int sub = 0; sub < NSUB; ++sub) kfa[sub][d0] = *(const LAS bf16x8*)(sb + (sub * 32 + r32) * KP + hi * 16 + d0 * 32);
;                 asm volatile("s_waitcnt lgkmcnt(0)" ::: "memory");
;                 __builtin_amdgcn_sched_barrier(0);
;                 __builtin_amdgcn_s_setprio(1);
; #pragma unroll
;                 for (int d0 = 0; d0 < DQK / 16; ++d0)
; #pragma unroll
;                     for (int sub = 0; sub < NSUB; ++sub) sc[0][sub] = __builtin_amdgcn_mfma_f32_32x32x16_bf16(kfa[sub][d0], qf[0][d0], sc[0][sub], 0, 0, 0);
;     ...
;                 if (MODE == 0) {
;                     if (st * 32 + 31 > q0) {
; #pragma unroll
;                         for (int r = 0; r < 16; ++r) { if (st * 32 + crow(r, hi) > q0 + r32) {
; #pragma unroll
;                             for (int qh = 0; qh < NQ; ++qh) sc[qh][sub][r] = -INFINITY; } }
;                     }
.LBB0_4304:
	s_cmp_gt_i32 s15, s25
	s_cbranch_scc1 .LBB0_4312
	s_bitcmp1_b32 s3, 0
	s_cselect_b32 s12, 0x5800, 0
	s_add_i32 s12, s12, 0
	v_add3_u32 v35, s12, v116, v156
	ds_read_b128 v[160:163], v35
	ds_read_b128 v[164:167], v35 offset:32
	ds_read_b128 v[168:171], v35 offset:6656
	ds_read_b128 v[172:175], v35 offset:6688
	ds_read_b128 v[176:179], v35 offset:64
	ds_read_b128 v[180:183], v35 offset:96
	ds_read_b128 v[184:187], v35 offset:6720
	ds_read_b128 v[188:191], v35 offset:6752
	ds_read_b128 v[192:195], v35 offset:128
	ds_read_b128 v[196:199], v35 offset:160
	ds_read_b128 v[200:203], v35 offset:6784
	ds_read_b128 v[204:207], v35 offset:6816
	s_waitcnt lgkmcnt(0)
	v_xor_b32_e32 v34, 0x80000000, v1
	s_setprio 1
	v_mov_b32_e32 v35, v34
	v_mov_b32_e32 v36, v34
	v_mov_b32_e32 v37, v34
	v_mov_b32_e32 v38, v34
	v_mov_b32_e32 v39, v34
	v_mov_b32_e32 v40, v34
	v_mov_b32_e32 v41, v34
	v_mov_b32_e32 v42, v34
	v_mov_b32_e32 v43, v34
	v_mov_b32_e32 v44, v34
	v_mov_b32_e32 v45, v34
	v_mov_b32_e32 v46, v34
	v_mov_b32_e32 v47, v34
	v_mov_b32_e32 v48, v34
	v_mov_b32_e32 v49, v34
	s_waitcnt lgkmcnt(11)
	s_nop 0
	v_mfma_f32_32x32x16_bf16 v[50:65], v[160:163], v[86:89], v[34:49]
	s_waitcnt lgkmcnt(9)
	v_mfma_f32_32x32x16_bf16 v[34:49], v[168:171], v[86:89], v[34:49]
	s_nop 0
	v_mfma_f32_32x32x16_bf16 v[50:65], v[164:167], v[82:85], v[50:65]
	s_waitcnt lgkmcnt(8)
	v_mfma_f32_32x32x16_bf16 v[34:49], v[172:175], v[82:85], v[34:49]
	s_waitcnt lgkmcnt(7)
	v_mfma_f32_32x32x16_bf16 v[50:65], v[176:179], v[78:81], v[50:65]
	s_waitcnt lgkmcnt(5)
	v_mfma_f32_32x32x16_bf16 v[34:49], v[184:187], v[78:81], v[34:49]
	s_nop 0
	v_mfma_f32_32x32x16_bf16 v[50:65], v[180:183], v[74:77], v[50:65]
	s_waitcnt lgkmcnt(4)
	v_mfma_f32_32x32x16_bf16 v[34:49], v[188:191], v[74:77], v[34:49]
	s_waitcnt lgkmcnt(3)
	v_mfma_f32_32x32x16_bf16 v[50:65], v[192:195], v[70:73], v[50:65]
	s_waitcnt lgkmcnt(1)
	v_mfma_f32_32x32x16_bf16 v[34:49], v[200:203], v[70:73], v[34:49]
	s_nop 0
	v_mfma_f32_32x32x16_bf16 v[50:65], v[196:199], v[66:69], v[50:65]
	s_waitcnt lgkmcnt(0)
	v_mfma_f32_32x32x16_bf16 v[34:49], v[204:207], v[66:69], v[34:49]
	s_setprio 0
	s_add_i32 s13, s17, 31
	s_cmp_le_i32 s13, s24
	v_add_u32_e32 v143, s17, v117
	s_cbranch_scc1 .LBB0_4307
	v_cmp_gt_i32_e32 vcc, v143, v141
	s_nop 3
	v_cndmask_b32_e32 v145, v50, v238, vcc
	v_cmp_lt_i32_e32 vcc, v143, v141
	s_nop 1
	v_cndmask_b32_e32 v50, v145, v50, vcc
	v_add_u32_e32 v145, 2, v143
	v_cndmask_b32_e32 v51, v238, v51, vcc
	v_cmp_le_i32_e32 vcc, v145, v141
	v_add_u32_e32 v145, 3, v143
	s_nop 0
	v_cndmask_b32_e32 v52, v238, v52, vcc
	v_cmp_le_i32_e32 vcc, v145, v141
	v_add_u32_e32 v145, 8, v143
	s_nop 0
	v_cndmask_b32_e32 v53, v238, v53, vcc
	v_cmp_le_i32_e32 vcc, v145, v141
	v_add_u32_e32 v145, 9, v143
	s_nop 0
	v_cndmask_b32_e32 v54, v238, v54, vcc
	v_cmp_le_i32_e32 vcc, v145, v141
	v_add_u32_e32 v145, 10, v143
	s_nop 0
	v_cndmask_b32_e32 v55, v238, v55, vcc
	v_cmp_le_i32_e32 vcc, v145, v141
	v_add_u32_e32 v145, 11, v143
	s_nop 0
	v_cndmask_b32_e32 v56, v238, v56, vcc
	v_cmp_le_i32_e32 vcc, v145, v141
	v_add_u32_e32 v145, 16, v143
	s_nop 0
	v_cndmask_b32_e32 v57, v238, v57, vcc
	v_cmp_le_i32_e32 vcc, v145, v141
	v_add_u32_e32 v145, 17, v143
	s_nop 0
	v_cndmask_b32_e32 v58, v238, v58, vcc
	v_cmp_le_i32_e32 vcc, v145, v141
	v_add_u32_e32 v145, 18, v143
	s_nop 0
	v_cndmask_b32_e32 v59, v238, v59, vcc
	v_cmp_le_i32_e32 vcc, v145, v141
	v_add_u32_e32 v145, 19, v143
	s_nop 0
	v_cndmask_b32_e32 v60, v238, v60, vcc
	v_cmp_le_i32_e32 vcc, v145, v141
	v_add_u32_e32 v145, 24, v143
	s_nop 0
	v_cndmask_b32_e32 v61, v238, v61, vcc
	v_cmp_le_i32_e32 vcc, v145, v141
	v_add_u32_e32 v145, 25, v143
	s_nop 0
	v_cndmask_b32_e32 v62, v238, v62, vcc
	v_cmp_le_i32_e32 vcc, v145, v141
	v_add_u32_e32 v145, 26, v143
	s_nop 0
	v_cndmask_b32_e32 v63, v238, v63, vcc
	v_cmp_le_i32_e32 vcc, v145, v141
	v_add_u32_e32 v145, 27, v143
	s_nop 0
	v_cndmask_b32_e32 v64, v238, v64, vcc
	v_cmp_le_i32_e32 vcc, v145, v141
	s_nop 1
	v_cndmask_b32_e32 v65, v238, v65, vcc
